# nt hint on P3 (input projection) output stores as well
# speedup vs baseline: 1.0031x; 1.0031x over previous
;     __device__ __forceinline__ void operator()(Acc& acc, const Unit& u, int wr, int wc, int fr, int fq) const {
;     ...
;             for (int m = 0; m < 4; ++m) {
;                 const int row = row0 + ai * HALF + m * 16;
;                 const float r = rs[u.idx * BM + wr * 64 + fr + ai * HALF + m * 16];
;                 if (gate_tile) {
;                     if (wc == 0 && fq == 0) { *(f32x4*)(gates + (size_t)row * 8) = acc[ai][0][m][0] * r; *(f32x4*)(gates + (size_t)row * 8 + 4) = acc[ai][0][m][1] * r; }
;                 } else if (u.pn >= 9) {
;                     const float c1 = -r * 1.4426950408889634f;
;                     f32x4 R[2], S[2];
; #pragma unroll
;                     for (int n = 0; n < 2; ++n) {
;                         const f32x4 tm = acc[ai][0][m][n] * c1, ta = acc[ai][1][m][n] * c1; f32x4 em, ea;
; #pragma unroll
;                         for (int i = 0; i < 4; ++i) { em[i] = __builtin_amdgcn_exp2f(tm[i]); ea[i] = __builtin_amdgcn_exp2f(ta[i]); }
;                         const f32x4 dm = em + 1.0f, da = ea + 1.0f; f32x4 qm, qa;
; #pragma unroll
;                         for (int i = 0; i < 4; ++i) { qm[i] = __builtin_amdgcn_rcpf(dm[i]); qa[i] = __builtin_amdgcn_rcpf(da[i]); }
;                         R[n] = da * qm; S[n] = qa;
;                     }
;                     const int gcol = (u.pn - 9) * HALF + wc * 32 + 8 * fq;
;                     u32x4 w; w.x = cvt_pk_bf16(R[0][0], R[0][1]); w.y = cvt_pk_bf16(R[0][2], R[0][3]); w.z = cvt_pk_bf16(R[1][0], R[1][1]); w.w = cvt_pk_bf16(R[1][2], R[1][3]);
;                     *(u32x4*)(P + (size_t)row * NIN + PC_GM + gcol) = w;
;                     w.x = cvt_pk_bf16(S[0][0], S[0][1]); w.y = cvt_pk_bf16(S[0][2], S[0][3]); w.z = cvt_pk_bf16(S[1][0], S[1][1]); w.w = cvt_pk_bf16(S[1][2], S[1][3]);
;                     *(u32x4*)(P + (size_t)row * NIN + PC_GA + gcol) = w;
;                 } else {
; #pragma unroll
;                     for (int bj = 0; bj < 2; ++bj) {
;                         const f32x4 v0 = acc[ai][bj][m][0] * r, v1 = acc[ai][bj][m][1] * r;
;                         u32x4 w; w.x = cvt_pk_bf16(v0[0], v0[1]); w.y = cvt_pk_bf16(v0[2], v0[3]); w.z = cvt_pk_bf16(v1[0], v1[1]); w.w = cvt_pk_bf16(v1[2], v1[3]);
;                         *(u32x4*)(P + (size_t)row * NIN + col0 + bj * HALF) = w;
;                     }
.LBB0_877:
	s_cmp_lg_u32 s8, 17
	s_cselect_b64 s[26:27], -1, 0
	v_lshl_add_u32 v148, s6, 8, v151
	s_lshl_b32 s6, s7, 10
	v_add_u32_e32 v161, s6, v157
	ds_read_b32 v150, v161
	v_lshl_or_b32 v146, s8, 8, v155
	v_ashrrev_i32_e32 v147, 31, v146
	s_mov_b64 s[6:7], -1
	s_and_b64 vcc, exec, s[26:27]
	s_cbranch_vccz .LBB0_883
	s_cmp_gt_i32 s8, 8
	s_cbranch_scc1 .LBB0_880
	s_waitcnt lgkmcnt(0)
	v_pk_mul_f32 v[164:165], v[118:119], v[150:151] op_sel_hi:[1,0]
	v_pk_mul_f32 v[162:163], v[116:117], v[150:151] op_sel_hi:[1,0]
	v_pk_mul_f32 v[166:167], v[114:115], v[150:151] op_sel_hi:[1,0]
	v_pk_mul_f32 v[168:169], v[112:113], v[150:151] op_sel_hi:[1,0]
	v_cvt_pk_bf16_f32 v162, v162, v163
	v_cvt_pk_bf16_f32 v163, v164, v165
	v_pk_mul_f32 v[170:171], v[120:121], v[150:151] op_sel_hi:[1,0]
	v_cvt_pk_bf16_f32 v164, v168, v169
	v_cvt_pk_bf16_f32 v165, v166, v167
	v_mov_b64_e32 v[166:167], s[68:69]
	v_mad_i64_i32 v[166:167], s[6:7], v148, s47, v[166:167]
	v_lshl_add_u64 v[166:167], v[146:147], 1, v[166:167]
	global_store_dwordx4 v[166:167], v[162:165], off nt
	s_mov_b64 s[6:7], 0
	v_pk_mul_f32 v[168:169], v[122:123], v[150:151] op_sel_hi:[1,0]
	v_pk_mul_f32 v[164:165], v[126:127], v[150:151] op_sel_hi:[1,0]
	v_pk_mul_f32 v[162:163], v[124:125], v[150:151] op_sel_hi:[1,0]
	s_nop 0
	v_cvt_pk_bf16_f32 v162, v162, v163
	v_cvt_pk_bf16_f32 v163, v164, v165
	v_cvt_pk_bf16_f32 v164, v170, v171
	v_cvt_pk_bf16_f32 v165, v168, v169
	global_store_dwordx4 v[166:167], v[162:165], off offset:256 nt
.LBB0_880:
	s_andn2_b64 vcc, exec, s[6:7]
	s_cbranch_vccnz .LBB0_882
	s_waitcnt lgkmcnt(0)
	v_mul_f32_e32 v136, 0xbfb8aa3b, v150
	v_mul_f32_e32 v162, v117, v136
	v_exp_f32_e32 v163, v162
	v_mul_f32_e32 v162, v118, v136
	v_mul_f32_e32 v149, v116, v136
	v_exp_f32_e32 v164, v162
	v_mul_f32_e32 v162, v119, v136
	v_exp_f32_e32 v149, v149
	v_exp_f32_e32 v165, v162
	v_mul_f32_e32 v124, v124, v136
	v_mul_f32_e32 v125, v125, v136
	v_mul_f32_e32 v126, v126, v136
	v_mul_f32_e32 v127, v127, v136
	v_exp_f32_e32 v124, v124
	v_exp_f32_e32 v125, v125
	v_exp_f32_e32 v126, v126
	v_exp_f32_e32 v127, v127
	v_add_f32_e32 v149, 1.0, v149
	v_add_f32_e32 v163, 1.0, v163
	v_add_f32_e32 v164, 1.0, v164
	v_add_f32_e32 v165, 1.0, v165
	v_rcp_f32_e32 v162, v149
	v_rcp_f32_e32 v163, v163
	v_rcp_f32_e32 v164, v164
	v_rcp_f32_e32 v165, v165
	v_pk_add_f32 v[126:127], v[126:127], 1.0 op_sel_hi:[1,0]
	v_pk_add_f32 v[124:125], v[124:125], 1.0 op_sel_hi:[1,0]
	v_rcp_f32_e32 v167, v126
	v_rcp_f32_e32 v149, v124
	v_rcp_f32_e32 v166, v125
	v_rcp_f32_e32 v168, v127
	v_pk_mul_f32 v[126:127], v[126:127], v[164:165]
	v_pk_mul_f32 v[124:125], v[124:125], v[162:163]
	v_mul_f32_e32 v162, v112, v136
	v_mul_f32_e32 v120, v120, v136
	v_mul_f32_e32 v163, v113, v136
	v_mul_f32_e32 v121, v121, v136
	v_mul_f32_e32 v164, v114, v136
	v_mul_f32_e32 v122, v122, v136
	v_mul_f32_e32 v123, v123, v136
	v_mul_f32_e32 v136, v115, v136
	v_exp_f32_e32 v162, v162
	v_exp_f32_e32 v163, v163
	v_exp_f32_e32 v164, v164
	v_exp_f32_e32 v136, v136
	v_exp_f32_e32 v120, v120
	v_exp_f32_e32 v121, v121
	v_exp_f32_e32 v122, v122
	v_exp_f32_e32 v123, v123
	v_add_f32_e32 v162, 1.0, v162
	v_add_f32_e32 v163, 1.0, v163
	v_add_f32_e32 v164, 1.0, v164
	v_add_f32_e32 v136, 1.0, v136
	v_rcp_f32_e32 v162, v162
	v_rcp_f32_e32 v163, v163
	v_rcp_f32_e32 v164, v164
	v_rcp_f32_e32 v165, v136
	v_pk_add_f32 v[122:123], v[122:123], 1.0 op_sel_hi:[1,0]
	v_pk_add_f32 v[120:121], v[120:121], 1.0 op_sel_hi:[1,0]
	v_rcp_f32_e32 v171, v122
	v_rcp_f32_e32 v169, v120
	v_rcp_f32_e32 v172, v123
	v_pk_mul_f32 v[164:165], v[122:123], v[164:165]
	v_pk_mul_f32 v[122:123], v[120:121], v[162:163]
	v_cvt_pk_bf16_f32 v120, v124, v125
	v_mov_b64_e32 v[124:125], s[68:69]
	v_lshl_add_u32 v136, s8, 7, v156
	v_mad_i64_i32 v[124:125], s[6:7], v148, s47, v[124:125]
	v_lshl_add_u64 v[124:125], v[136:137], 1, v[124:125]
	v_add_co_u32_e32 v124, vcc, 0x1000, v124
	v_rcp_f32_e32 v170, v121
	v_cvt_pk_bf16_f32 v121, v126, v127
	v_cvt_pk_bf16_f32 v122, v122, v123
	v_cvt_pk_bf16_f32 v123, v164, v165
	s_nop 0
	v_addc_co_u32_e32 v125, vcc, 0, v125, vcc
	global_store_dwordx4 v[124:125], v[120:123], off offset:512 nt
	s_nop 1
	v_cvt_pk_bf16_f32 v120, v149, v166
	v_cvt_pk_bf16_f32 v121, v167, v168
	v_cvt_pk_bf16_f32 v122, v169, v170
	v_cvt_pk_bf16_f32 v123, v171, v172
	global_store_dwordx4 v[124:125], v[120:123], off offset:2560 nt

;     __device__ __forceinline__ void operator()(Acc& acc, const Unit& u, int wr, int wc, int fr, int fq) const {
;     ...
;                 if (gate_tile) {
;                     if (wc == 0 && fq == 0) { *(f32x4*)(gates + (size_t)row * 8) = acc[ai][0][m][0] * r; *(f32x4*)(gates + (size_t)row * 8 + 4) = acc[ai][0][m][1] * r; }
.LBB0_883:
	s_andn2_b64 vcc, exec, s[6:7]
	s_cbranch_vccnz .LBB0_887
	s_and_saveexec_b64 s[6:7], s[2:3]
	s_cbranch_execz .LBB0_886
	v_ashrrev_i32_e32 v149, 31, v148
	v_lshlrev_b64 v[120:121], 5, v[148:149]
	v_lshl_add_u64 v[120:121], s[12:13], 0, v[120:121]
	s_waitcnt lgkmcnt(0)
	v_pk_mul_f32 v[118:119], v[118:119], v[150:151] op_sel_hi:[1,0]
	v_pk_mul_f32 v[116:117], v[116:117], v[150:151] op_sel_hi:[1,0]
	v_pk_mul_f32 v[114:115], v[114:115], v[150:151] op_sel_hi:[1,0]
	v_pk_mul_f32 v[112:113], v[112:113], v[150:151] op_sel_hi:[1,0]
	global_store_dwordx4 v[120:121], v[116:119], off nt
	global_store_dwordx4 v[120:121], v[112:115], off offset:16 nt

;     __device__ __forceinline__ void operator()(Acc& acc, const Unit& u, int wr, int wc, int fr, int fq) const {
;     ...
;             for (int m = 0; m < 4; ++m) {
;                 const int row = row0 + ai * HALF + m * 16;
;                 const float r = rs[u.idx * BM + wr * 64 + fr + ai * HALF + m * 16];
;                 if (gate_tile) {
;                     if (wc == 0 && fq == 0) { *(f32x4*)(gates + (size_t)row * 8) = acc[ai][0][m][0] * r; *(f32x4*)(gates + (size_t)row * 8 + 4) = acc[ai][0][m][1] * r; }
;                 } else if (u.pn >= 9) {
;                     const float c1 = -r * 1.4426950408889634f;
;                     f32x4 R[2], S[2];
; #pragma unroll
;                     for (int n = 0; n < 2; ++n) {
;                         const f32x4 tm = acc[ai][0][m][n] * c1, ta = acc[ai][1][m][n] * c1; f32x4 em, ea;
; #pragma unroll
;                         for (int i = 0; i < 4; ++i) { em[i] = __builtin_amdgcn_exp2f(tm[i]); ea[i] = __builtin_amdgcn_exp2f(ta[i]); }
;                         const f32x4 dm = em + 1.0f, da = ea + 1.0f; f32x4 qm, qa;
; #pragma unroll
;                         for (int i = 0; i < 4; ++i) { qm[i] = __builtin_amdgcn_rcpf(dm[i]); qa[i] = __builtin_amdgcn_rcpf(da[i]); }
;                         R[n] = da * qm; S[n] = qa;
;                     }
;                     const int gcol = (u.pn - 9) * HALF + wc * 32 + 8 * fq;
;                     u32x4 w; w.x = cvt_pk_bf16(R[0][0], R[0][1]); w.y = cvt_pk_bf16(R[0][2], R[0][3]); w.z = cvt_pk_bf16(R[1][0], R[1][1]); w.w = cvt_pk_bf16(R[1][2], R[1][3]);
;                     *(u32x4*)(P + (size_t)row * NIN + PC_GM + gcol) = w;
;                     w.x = cvt_pk_bf16(S[0][0], S[0][1]); w.y = cvt_pk_bf16(S[0][2], S[0][3]); w.z = cvt_pk_bf16(S[1][0], S[1][1]); w.w = cvt_pk_bf16(S[1][2], S[1][3]);
;                     *(u32x4*)(P + (size_t)row * NIN + PC_GA + gcol) = w;
;                 } else {
; #pragma unroll
;                     for (int bj = 0; bj < 2; ++bj) {
;                         const f32x4 v0 = acc[ai][bj][m][0] * r, v1 = acc[ai][bj][m][1] * r;
;                         u32x4 w; w.x = cvt_pk_bf16(v0[0], v0[1]); w.y = cvt_pk_bf16(v0[2], v0[3]); w.z = cvt_pk_bf16(v1[0], v1[1]); w.w = cvt_pk_bf16(v1[2], v1[3]);
;                         *(u32x4*)(P + (size_t)row * NIN + col0 + bj * HALF) = w;
;                     }
.LBB0_887:
	ds_read_b32 v112, v161 offset:64
	v_cndmask_b32_e64 v113, 0, 1, s[26:27]
	v_or_b32_e32 v114, 16, v148
	v_cmp_ne_u32_e64 s[6:7], 1, v113
	s_andn2_b64 vcc, exec, s[26:27]
	s_mov_b64 s[26:27], -1
	s_cbranch_vccnz .LBB0_893
	s_cmp_gt_i32 s8, 8
	s_cbranch_scc1 .LBB0_890
	s_waitcnt lgkmcnt(0)
	v_pk_mul_f32 v[118:119], v[102:103], v[112:113] op_sel_hi:[1,0]
	v_pk_mul_f32 v[116:117], v[100:101], v[112:113] op_sel_hi:[1,0]
	v_pk_mul_f32 v[120:121], v[98:99], v[112:113] op_sel_hi:[1,0]
	v_pk_mul_f32 v[122:123], v[96:97], v[112:113] op_sel_hi:[1,0]
	v_cvt_pk_bf16_f32 v116, v116, v117
	v_cvt_pk_bf16_f32 v117, v118, v119
	v_pk_mul_f32 v[124:125], v[104:105], v[112:113] op_sel_hi:[1,0]
	v_cvt_pk_bf16_f32 v118, v122, v123
	v_cvt_pk_bf16_f32 v119, v120, v121
	v_mov_b64_e32 v[120:121], s[68:69]
	v_mad_i64_i32 v[120:121], s[26:27], v114, s47, v[120:121]
	v_lshl_add_u64 v[120:121], v[146:147], 1, v[120:121]
	global_store_dwordx4 v[120:121], v[116:119], off nt
	s_mov_b64 s[26:27], 0
	v_pk_mul_f32 v[122:123], v[106:107], v[112:113] op_sel_hi:[1,0]
	v_pk_mul_f32 v[118:119], v[110:111], v[112:113] op_sel_hi:[1,0]
	v_pk_mul_f32 v[116:117], v[108:109], v[112:113] op_sel_hi:[1,0]
	s_nop 0
	v_cvt_pk_bf16_f32 v116, v116, v117
	v_cvt_pk_bf16_f32 v117, v118, v119
	v_cvt_pk_bf16_f32 v118, v124, v125
	v_cvt_pk_bf16_f32 v119, v122, v123
	global_store_dwordx4 v[120:121], v[116:119], off offset:256 nt
.LBB0_890:
	s_andn2_b64 vcc, exec, s[26:27]
	s_cbranch_vccnz .LBB0_892
	s_waitcnt lgkmcnt(0)
	v_mul_f32_e32 v113, 0xbfb8aa3b, v112
	v_mul_f32_e32 v116, v101, v113
	v_exp_f32_e32 v117, v116
	v_mul_f32_e32 v116, v102, v113
	v_mul_f32_e32 v115, v100, v113
	v_exp_f32_e32 v118, v116
	v_mul_f32_e32 v116, v103, v113
	v_exp_f32_e32 v115, v115
	v_exp_f32_e32 v119, v116
	v_mul_f32_e32 v108, v108, v113
	v_mul_f32_e32 v109, v109, v113
	v_mul_f32_e32 v110, v110, v113
	v_mul_f32_e32 v111, v111, v113
	v_exp_f32_e32 v108, v108
	v_exp_f32_e32 v109, v109
	v_exp_f32_e32 v110, v110
	v_exp_f32_e32 v111, v111
	v_add_f32_e32 v115, 1.0, v115
	v_add_f32_e32 v117, 1.0, v117
	v_add_f32_e32 v118, 1.0, v118
	v_add_f32_e32 v119, 1.0, v119
	v_rcp_f32_e32 v116, v115
	v_rcp_f32_e32 v117, v117
	v_rcp_f32_e32 v118, v118
	v_rcp_f32_e32 v119, v119
	v_pk_add_f32 v[110:111], v[110:111], 1.0 op_sel_hi:[1,0]
	v_pk_add_f32 v[108:109], v[108:109], 1.0 op_sel_hi:[1,0]
	v_rcp_f32_e32 v121, v110
	v_rcp_f32_e32 v115, v108
	v_rcp_f32_e32 v120, v109
	v_rcp_f32_e32 v122, v111
	v_pk_mul_f32 v[110:111], v[110:111], v[118:119]
	v_pk_mul_f32 v[108:109], v[108:109], v[116:117]
	v_mul_f32_e32 v116, v96, v113
	v_mul_f32_e32 v104, v104, v113
	v_mul_f32_e32 v117, v97, v113
	v_mul_f32_e32 v105, v105, v113
	v_mul_f32_e32 v118, v98, v113
	v_mul_f32_e32 v106, v106, v113
	v_mul_f32_e32 v107, v107, v113
	v_mul_f32_e32 v113, v99, v113
	v_exp_f32_e32 v116, v116
	v_exp_f32_e32 v117, v117
	v_exp_f32_e32 v118, v118
	v_exp_f32_e32 v113, v113
	v_exp_f32_e32 v104, v104
	v_exp_f32_e32 v105, v105
	v_exp_f32_e32 v106, v106
	v_exp_f32_e32 v107, v107
	v_add_f32_e32 v116, 1.0, v116
	v_add_f32_e32 v117, 1.0, v117
	v_add_f32_e32 v118, 1.0, v118
	v_add_f32_e32 v113, 1.0, v113
	v_rcp_f32_e32 v116, v116
	v_rcp_f32_e32 v117, v117
	v_rcp_f32_e32 v118, v118
	v_rcp_f32_e32 v119, v113
	v_pk_add_f32 v[106:107], v[106:107], 1.0 op_sel_hi:[1,0]
	v_pk_add_f32 v[104:105], v[104:105], 1.0 op_sel_hi:[1,0]
	v_rcp_f32_e32 v124, v106
	v_rcp_f32_e32 v123, v104
	v_rcp_f32_e32 v125, v107
	v_pk_mul_f32 v[118:119], v[106:107], v[118:119]
	v_pk_mul_f32 v[106:107], v[104:105], v[116:117]
	v_cvt_pk_bf16_f32 v104, v108, v109
	v_mov_b64_e32 v[108:109], s[68:69]
	v_lshl_add_u32 v136, s8, 7, v156
	v_mad_i64_i32 v[108:109], s[26:27], v114, s47, v[108:109]
	v_lshl_add_u64 v[108:109], v[136:137], 1, v[108:109]
	v_add_co_u32_e32 v108, vcc, 0x1000, v108
	v_rcp_f32_e32 v113, v105
	v_cvt_pk_bf16_f32 v105, v110, v111
	v_cvt_pk_bf16_f32 v106, v106, v107
	v_cvt_pk_bf16_f32 v107, v118, v119
	s_nop 0
	v_addc_co_u32_e32 v109, vcc, 0, v109, vcc
	global_store_dwordx4 v[108:109], v[104:107], off offset:512 nt
	s_nop 1
	v_cvt_pk_bf16_f32 v104, v115, v120
	v_cvt_pk_bf16_f32 v105, v121, v122
	v_cvt_pk_bf16_f32 v106, v123, v113
	v_cvt_pk_bf16_f32 v107, v124, v125
	global_store_dwordx4 v[108:109], v[104:107], off offset:2560 nt

;     __device__ __forceinline__ void operator()(Acc& acc, const Unit& u, int wr, int wc, int fr, int fq) const {
;     ...
;                 if (gate_tile) {
;                     if (wc == 0 && fq == 0) { *(f32x4*)(gates + (size_t)row * 8) = acc[ai][0][m][0] * r; *(f32x4*)(gates + (size_t)row * 8 + 4) = acc[ai][0][m][1] * r; }
.LBB0_893:
	s_andn2_b64 vcc, exec, s[26:27]
	s_cbranch_vccnz .LBB0_897
	s_and_saveexec_b64 s[26:27], s[2:3]
	s_cbranch_execz .LBB0_896
	v_ashrrev_i32_e32 v115, 31, v114
	v_lshlrev_b64 v[104:105], 5, v[114:115]
	v_lshl_add_u64 v[104:105], s[12:13], 0, v[104:105]
	s_waitcnt lgkmcnt(0)
	v_pk_mul_f32 v[102:103], v[102:103], v[112:113] op_sel_hi:[1,0]
	v_pk_mul_f32 v[100:101], v[100:101], v[112:113] op_sel_hi:[1,0]
	v_pk_mul_f32 v[98:99], v[98:99], v[112:113] op_sel_hi:[1,0]
	v_pk_mul_f32 v[96:97], v[96:97], v[112:113] op_sel_hi:[1,0]
	global_store_dwordx4 v[104:105], v[100:103], off nt
	global_store_dwordx4 v[104:105], v[96:99], off offset:16 nt

;     __device__ __forceinline__ void operator()(Acc& acc, const Unit& u, int wr, int wc, int fr, int fq) const {
;     ...
;             for (int m = 0; m < 4; ++m) {
;                 const int row = row0 + ai * HALF + m * 16;
;                 const float r = rs[u.idx * BM + wr * 64 + fr + ai * HALF + m * 16];
;                 if (gate_tile) {
;                     if (wc == 0 && fq == 0) { *(f32x4*)(gates + (size_t)row * 8) = acc[ai][0][m][0] * r; *(f32x4*)(gates + (size_t)row * 8 + 4) = acc[ai][0][m][1] * r; }
;                 } else if (u.pn >= 9) {
;                     const float c1 = -r * 1.4426950408889634f;
;                     f32x4 R[2], S[2];
; #pragma unroll
;                     for (int n = 0; n < 2; ++n) {
;                         const f32x4 tm = acc[ai][0][m][n] * c1, ta = acc[ai][1][m][n] * c1; f32x4 em, ea;
; #pragma unroll
;                         for (int i = 0; i < 4; ++i) { em[i] = __builtin_amdgcn_exp2f(tm[i]); ea[i] = __builtin_amdgcn_exp2f(ta[i]); }
;                         const f32x4 dm = em + 1.0f, da = ea + 1.0f; f32x4 qm, qa;
; #pragma unroll
;                         for (int i = 0; i < 4; ++i) { qm[i] = __builtin_amdgcn_rcpf(dm[i]); qa[i] = __builtin_amdgcn_rcpf(da[i]); }
;                         R[n] = da * qm; S[n] = qa;
;                     }
;                     const int gcol = (u.pn - 9) * HALF + wc * 32 + 8 * fq;
;                     u32x4 w; w.x = cvt_pk_bf16(R[0][0], R[0][1]); w.y = cvt_pk_bf16(R[0][2], R[0][3]); w.z = cvt_pk_bf16(R[1][0], R[1][1]); w.w = cvt_pk_bf16(R[1][2], R[1][3]);
;                     *(u32x4*)(P + (size_t)row * NIN + PC_GM + gcol) = w;
;                     w.x = cvt_pk_bf16(S[0][0], S[0][1]); w.y = cvt_pk_bf16(S[0][2], S[0][3]); w.z = cvt_pk_bf16(S[1][0], S[1][1]); w.w = cvt_pk_bf16(S[1][2], S[1][3]);
;                     *(u32x4*)(P + (size_t)row * NIN + PC_GA + gcol) = w;
;                 } else {
; #pragma unroll
;                     for (int bj = 0; bj < 2; ++bj) {
;                         const f32x4 v0 = acc[ai][bj][m][0] * r, v1 = acc[ai][bj][m][1] * r;
;                         u32x4 w; w.x = cvt_pk_bf16(v0[0], v0[1]); w.y = cvt_pk_bf16(v0[2], v0[3]); w.z = cvt_pk_bf16(v1[0], v1[1]); w.w = cvt_pk_bf16(v1[2], v1[3]);
;                         *(u32x4*)(P + (size_t)row * NIN + col0 + bj * HALF) = w;
;                     }
.LBB0_897:
	ds_read_b32 v96, v161 offset:128
	v_or_b32_e32 v98, 32, v148
	s_and_b64 vcc, exec, s[6:7]
	s_mov_b64 s[26:27], -1
	s_cbranch_vccnz .LBB0_903
	s_cmp_gt_i32 s8, 8
	s_cbranch_scc1 .LBB0_900
	s_waitcnt lgkmcnt(0)
	v_pk_mul_f32 v[102:103], v[86:87], v[96:97] op_sel_hi:[1,0]
	v_pk_mul_f32 v[100:101], v[84:85], v[96:97] op_sel_hi:[1,0]
	v_pk_mul_f32 v[104:105], v[82:83], v[96:97] op_sel_hi:[1,0]
	v_pk_mul_f32 v[106:107], v[80:81], v[96:97] op_sel_hi:[1,0]
	v_cvt_pk_bf16_f32 v100, v100, v101
	v_cvt_pk_bf16_f32 v101, v102, v103
	v_pk_mul_f32 v[108:109], v[88:89], v[96:97] op_sel_hi:[1,0]
	v_cvt_pk_bf16_f32 v102, v106, v107
	v_cvt_pk_bf16_f32 v103, v104, v105
	v_mov_b64_e32 v[104:105], s[68:69]
	v_mad_i64_i32 v[104:105], s[26:27], v98, s47, v[104:105]
	v_lshl_add_u64 v[104:105], v[146:147], 1, v[104:105]
	global_store_dwordx4 v[104:105], v[100:103], off nt
	s_mov_b64 s[26:27], 0
	v_pk_mul_f32 v[106:107], v[90:91], v[96:97] op_sel_hi:[1,0]
	v_pk_mul_f32 v[102:103], v[94:95], v[96:97] op_sel_hi:[1,0]
	v_pk_mul_f32 v[100:101], v[92:93], v[96:97] op_sel_hi:[1,0]
	s_nop 0
	v_cvt_pk_bf16_f32 v100, v100, v101
	v_cvt_pk_bf16_f32 v101, v102, v103
	v_cvt_pk_bf16_f32 v102, v108, v109
	v_cvt_pk_bf16_f32 v103, v106, v107
	global_store_dwordx4 v[104:105], v[100:103], off offset:256 nt
.LBB0_900:
	s_andn2_b64 vcc, exec, s[26:27]
	s_cbranch_vccnz .LBB0_902
	s_waitcnt lgkmcnt(0)
	v_mul_f32_e32 v97, 0xbfb8aa3b, v96
	v_mul_f32_e32 v100, v85, v97
	v_exp_f32_e32 v101, v100
	v_mul_f32_e32 v100, v86, v97
	v_mul_f32_e32 v99, v84, v97
	v_exp_f32_e32 v102, v100
	v_mul_f32_e32 v100, v87, v97
	v_exp_f32_e32 v99, v99
	v_exp_f32_e32 v103, v100
	v_mul_f32_e32 v92, v92, v97
	v_mul_f32_e32 v93, v93, v97
	v_mul_f32_e32 v94, v94, v97
	v_mul_f32_e32 v95, v95, v97
	v_exp_f32_e32 v92, v92
	v_exp_f32_e32 v93, v93
	v_exp_f32_e32 v94, v94
	v_exp_f32_e32 v95, v95
	v_add_f32_e32 v99, 1.0, v99
	v_add_f32_e32 v101, 1.0, v101
	v_add_f32_e32 v102, 1.0, v102
	v_add_f32_e32 v103, 1.0, v103
	v_rcp_f32_e32 v100, v99
	v_rcp_f32_e32 v101, v101
	v_rcp_f32_e32 v102, v102
	v_rcp_f32_e32 v103, v103
	v_pk_add_f32 v[94:95], v[94:95], 1.0 op_sel_hi:[1,0]
	v_pk_add_f32 v[92:93], v[92:93], 1.0 op_sel_hi:[1,0]
	v_rcp_f32_e32 v105, v94
	v_rcp_f32_e32 v99, v92
	v_rcp_f32_e32 v104, v93
	v_rcp_f32_e32 v106, v95
	v_pk_mul_f32 v[94:95], v[94:95], v[102:103]
	v_pk_mul_f32 v[92:93], v[92:93], v[100:101]
	v_mul_f32_e32 v100, v80, v97
	v_mul_f32_e32 v88, v88, v97
	v_mul_f32_e32 v101, v81, v97
	v_mul_f32_e32 v89, v89, v97
	v_mul_f32_e32 v102, v82, v97
	v_mul_f32_e32 v90, v90, v97
	v_mul_f32_e32 v91, v91, v97
	v_mul_f32_e32 v97, v83, v97
	v_exp_f32_e32 v100, v100
	v_exp_f32_e32 v101, v101
	v_exp_f32_e32 v102, v102
	v_exp_f32_e32 v97, v97
	v_exp_f32_e32 v88, v88
	v_exp_f32_e32 v89, v89
	v_exp_f32_e32 v90, v90
	v_exp_f32_e32 v91, v91
	v_add_f32_e32 v100, 1.0, v100
	v_add_f32_e32 v101, 1.0, v101
	v_add_f32_e32 v102, 1.0, v102
	v_add_f32_e32 v97, 1.0, v97
	v_rcp_f32_e32 v100, v100
	v_rcp_f32_e32 v101, v101
	v_rcp_f32_e32 v102, v102
	v_rcp_f32_e32 v103, v97
	v_pk_add_f32 v[90:91], v[90:91], 1.0 op_sel_hi:[1,0]
	v_pk_add_f32 v[88:89], v[88:89], 1.0 op_sel_hi:[1,0]
	v_rcp_f32_e32 v108, v90
	v_rcp_f32_e32 v107, v88
	v_rcp_f32_e32 v109, v91
	v_pk_mul_f32 v[102:103], v[90:91], v[102:103]
	v_pk_mul_f32 v[90:91], v[88:89], v[100:101]
	v_cvt_pk_bf16_f32 v88, v92, v93
	v_mov_b64_e32 v[92:93], s[68:69]
	v_lshl_add_u32 v136, s8, 7, v156
	v_mad_i64_i32 v[92:93], s[26:27], v98, s47, v[92:93]
	v_lshl_add_u64 v[92:93], v[136:137], 1, v[92:93]
	v_add_co_u32_e32 v92, vcc, 0x1000, v92
	v_rcp_f32_e32 v97, v89
	v_cvt_pk_bf16_f32 v89, v94, v95
	v_cvt_pk_bf16_f32 v90, v90, v91
	v_cvt_pk_bf16_f32 v91, v102, v103
	s_nop 0
	v_addc_co_u32_e32 v93, vcc, 0, v93, vcc
	global_store_dwordx4 v[92:93], v[88:91], off offset:512 nt
	s_nop 1
	v_cvt_pk_bf16_f32 v88, v99, v104
	v_cvt_pk_bf16_f32 v89, v105, v106
	v_cvt_pk_bf16_f32 v90, v107, v97
	v_cvt_pk_bf16_f32 v91, v108, v109
	global_store_dwordx4 v[92:93], v[88:91], off offset:2560 nt

;     __device__ __forceinline__ void operator()(Acc& acc, const Unit& u, int wr, int wc, int fr, int fq) const {
;     ...
;                 if (gate_tile) {
;                     if (wc == 0 && fq == 0) { *(f32x4*)(gates + (size_t)row * 8) = acc[ai][0][m][0] * r; *(f32x4*)(gates + (size_t)row * 8 + 4) = acc[ai][0][m][1] * r; }
.LBB0_903:
	s_andn2_b64 vcc, exec, s[26:27]
	s_cbranch_vccnz .LBB0_907
	s_and_saveexec_b64 s[26:27], s[2:3]
	s_cbranch_execz .LBB0_906
	v_ashrrev_i32_e32 v99, 31, v98
	v_lshlrev_b64 v[88:89], 5, v[98:99]
	v_lshl_add_u64 v[88:89], s[12:13], 0, v[88:89]
	s_waitcnt lgkmcnt(0)
	v_pk_mul_f32 v[86:87], v[86:87], v[96:97] op_sel_hi:[1,0]
	v_pk_mul_f32 v[84:85], v[84:85], v[96:97] op_sel_hi:[1,0]
	v_pk_mul_f32 v[82:83], v[82:83], v[96:97] op_sel_hi:[1,0]
	v_pk_mul_f32 v[80:81], v[80:81], v[96:97] op_sel_hi:[1,0]
	global_store_dwordx4 v[88:89], v[84:87], off nt
	global_store_dwordx4 v[88:89], v[80:83], off offset:16 nt

;     __device__ __forceinline__ void operator()(Acc& acc, const Unit& u, int wr, int wc, int fr, int fq) const {
;     ...
;             for (int m = 0; m < 4; ++m) {
;                 const int row = row0 + ai * HALF + m * 16;
;                 const float r = rs[u.idx * BM + wr * 64 + fr + ai * HALF + m * 16];
;                 if (gate_tile) {
;                     if (wc == 0 && fq == 0) { *(f32x4*)(gates + (size_t)row * 8) = acc[ai][0][m][0] * r; *(f32x4*)(gates + (size_t)row * 8 + 4) = acc[ai][0][m][1] * r; }
;                 } else if (u.pn >= 9) {
;                     const float c1 = -r * 1.4426950408889634f;
;                     f32x4 R[2], S[2];
; #pragma unroll
;                     for (int n = 0; n < 2; ++n) {
;                         const f32x4 tm = acc[ai][0][m][n] * c1, ta = acc[ai][1][m][n] * c1; f32x4 em, ea;
; #pragma unroll
;                         for (int i = 0; i < 4; ++i) { em[i] = __builtin_amdgcn_exp2f(tm[i]); ea[i] = __builtin_amdgcn_exp2f(ta[i]); }
;                         const f32x4 dm = em + 1.0f, da = ea + 1.0f; f32x4 qm, qa;
; #pragma unroll
;                         for (int i = 0; i < 4; ++i) { qm[i] = __builtin_amdgcn_rcpf(dm[i]); qa[i] = __builtin_amdgcn_rcpf(da[i]); }
;                         R[n] = da * qm; S[n] = qa;
;                     }
;                     const int gcol = (u.pn - 9) * HALF + wc * 32 + 8 * fq;
;                     u32x4 w; w.x = cvt_pk_bf16(R[0][0], R[0][1]); w.y = cvt_pk_bf16(R[0][2], R[0][3]); w.z = cvt_pk_bf16(R[1][0], R[1][1]); w.w = cvt_pk_bf16(R[1][2], R[1][3]);
;                     *(u32x4*)(P + (size_t)row * NIN + PC_GM + gcol) = w;
;                     w.x = cvt_pk_bf16(S[0][0], S[0][1]); w.y = cvt_pk_bf16(S[0][2], S[0][3]); w.z = cvt_pk_bf16(S[1][0], S[1][1]); w.w = cvt_pk_bf16(S[1][2], S[1][3]);
;                     *(u32x4*)(P + (size_t)row * NIN + PC_GA + gcol) = w;
;                 } else {
; #pragma unroll
;                     for (int bj = 0; bj < 2; ++bj) {
;                         const f32x4 v0 = acc[ai][bj][m][0] * r, v1 = acc[ai][bj][m][1] * r;
;                         u32x4 w; w.x = cvt_pk_bf16(v0[0], v0[1]); w.y = cvt_pk_bf16(v0[2], v0[3]); w.z = cvt_pk_bf16(v1[0], v1[1]); w.w = cvt_pk_bf16(v1[2], v1[3]);
;                         *(u32x4*)(P + (size_t)row * NIN + col0 + bj * HALF) = w;
;                     }
.LBB0_907:
	ds_read_b32 v80, v161 offset:192
	v_or_b32_e32 v82, 48, v148
	s_and_b64 vcc, exec, s[6:7]
	s_mov_b64 s[26:27], -1
	s_cbranch_vccnz .LBB0_913
	s_cmp_gt_i32 s8, 8
	s_cbranch_scc1 .LBB0_910
	s_waitcnt lgkmcnt(0)
	v_pk_mul_f32 v[86:87], v[70:71], v[80:81] op_sel_hi:[1,0]
	v_pk_mul_f32 v[84:85], v[68:69], v[80:81] op_sel_hi:[1,0]
	v_pk_mul_f32 v[88:89], v[66:67], v[80:81] op_sel_hi:[1,0]
	v_pk_mul_f32 v[90:91], v[64:65], v[80:81] op_sel_hi:[1,0]
	v_cvt_pk_bf16_f32 v84, v84, v85
	v_cvt_pk_bf16_f32 v85, v86, v87
	v_pk_mul_f32 v[92:93], v[72:73], v[80:81] op_sel_hi:[1,0]
	v_cvt_pk_bf16_f32 v86, v90, v91
	v_cvt_pk_bf16_f32 v87, v88, v89
	v_mov_b64_e32 v[88:89], s[68:69]
	v_mad_i64_i32 v[88:89], s[26:27], v82, s47, v[88:89]
	v_lshl_add_u64 v[88:89], v[146:147], 1, v[88:89]
	global_store_dwordx4 v[88:89], v[84:87], off nt
	s_mov_b64 s[26:27], 0
	v_pk_mul_f32 v[90:91], v[74:75], v[80:81] op_sel_hi:[1,0]
	v_pk_mul_f32 v[86:87], v[78:79], v[80:81] op_sel_hi:[1,0]
	v_pk_mul_f32 v[84:85], v[76:77], v[80:81] op_sel_hi:[1,0]
	s_nop 0
	v_cvt_pk_bf16_f32 v84, v84, v85
	v_cvt_pk_bf16_f32 v85, v86, v87
	v_cvt_pk_bf16_f32 v86, v92, v93
	v_cvt_pk_bf16_f32 v87, v90, v91
	global_store_dwordx4 v[88:89], v[84:87], off offset:256 nt
.LBB0_910:
	s_andn2_b64 vcc, exec, s[26:27]
	s_cbranch_vccnz .LBB0_912
	s_waitcnt lgkmcnt(0)
	v_mul_f32_e32 v81, 0xbfb8aa3b, v80
	v_mul_f32_e32 v84, v69, v81
	v_exp_f32_e32 v85, v84
	v_mul_f32_e32 v84, v70, v81
	v_mul_f32_e32 v83, v68, v81
	v_exp_f32_e32 v86, v84
	v_mul_f32_e32 v84, v71, v81
	v_exp_f32_e32 v83, v83
	v_exp_f32_e32 v87, v84
	v_mul_f32_e32 v76, v76, v81
	v_mul_f32_e32 v77, v77, v81
	v_mul_f32_e32 v78, v78, v81
	v_mul_f32_e32 v79, v79, v81
	v_exp_f32_e32 v76, v76
	v_exp_f32_e32 v77, v77
	v_exp_f32_e32 v78, v78
	v_exp_f32_e32 v79, v79
	v_add_f32_e32 v83, 1.0, v83
	v_add_f32_e32 v85, 1.0, v85
	v_add_f32_e32 v86, 1.0, v86
	v_add_f32_e32 v87, 1.0, v87
	v_rcp_f32_e32 v84, v83
	v_rcp_f32_e32 v85, v85
	v_rcp_f32_e32 v86, v86
	v_rcp_f32_e32 v87, v87
	v_pk_add_f32 v[78:79], v[78:79], 1.0 op_sel_hi:[1,0]
	v_pk_add_f32 v[76:77], v[76:77], 1.0 op_sel_hi:[1,0]
	v_rcp_f32_e32 v89, v78
	v_rcp_f32_e32 v83, v76
	v_rcp_f32_e32 v88, v77
	v_rcp_f32_e32 v90, v79
	v_pk_mul_f32 v[78:79], v[78:79], v[86:87]
	v_pk_mul_f32 v[76:77], v[76:77], v[84:85]
	v_mul_f32_e32 v84, v64, v81
	v_mul_f32_e32 v72, v72, v81
	v_mul_f32_e32 v85, v65, v81
	v_mul_f32_e32 v73, v73, v81
	v_mul_f32_e32 v86, v66, v81
	v_mul_f32_e32 v74, v74, v81
	v_mul_f32_e32 v75, v75, v81
	v_mul_f32_e32 v81, v67, v81
	v_exp_f32_e32 v84, v84
	v_exp_f32_e32 v85, v85
	v_exp_f32_e32 v86, v86
	v_exp_f32_e32 v81, v81
	v_exp_f32_e32 v72, v72
	v_exp_f32_e32 v73, v73
	v_exp_f32_e32 v74, v74
	v_exp_f32_e32 v75, v75
	v_add_f32_e32 v84, 1.0, v84
	v_add_f32_e32 v85, 1.0, v85
	v_add_f32_e32 v86, 1.0, v86
	v_add_f32_e32 v81, 1.0, v81
	v_rcp_f32_e32 v84, v84
	v_rcp_f32_e32 v85, v85
	v_rcp_f32_e32 v86, v86
	v_rcp_f32_e32 v87, v81
	v_pk_add_f32 v[74:75], v[74:75], 1.0 op_sel_hi:[1,0]
	v_pk_add_f32 v[72:73], v[72:73], 1.0 op_sel_hi:[1,0]
	v_rcp_f32_e32 v92, v74
	v_rcp_f32_e32 v91, v72
	v_rcp_f32_e32 v93, v75
	v_pk_mul_f32 v[86:87], v[74:75], v[86:87]
	v_pk_mul_f32 v[74:75], v[72:73], v[84:85]
	v_cvt_pk_bf16_f32 v72, v76, v77
	v_mov_b64_e32 v[76:77], s[68:69]
	v_lshl_add_u32 v136, s8, 7, v156
	v_mad_i64_i32 v[76:77], s[26:27], v82, s47, v[76:77]
	v_lshl_add_u64 v[76:77], v[136:137], 1, v[76:77]
	v_add_co_u32_e32 v76, vcc, 0x1000, v76
	v_rcp_f32_e32 v81, v73
	v_cvt_pk_bf16_f32 v73, v78, v79
	v_cvt_pk_bf16_f32 v74, v74, v75
	v_cvt_pk_bf16_f32 v75, v86, v87
	s_nop 0
	v_addc_co_u32_e32 v77, vcc, 0, v77, vcc
	global_store_dwordx4 v[76:77], v[72:75], off offset:512 nt
	s_nop 1
	v_cvt_pk_bf16_f32 v72, v83, v88
	v_cvt_pk_bf16_f32 v73, v89, v90
	v_cvt_pk_bf16_f32 v74, v91, v81
	v_cvt_pk_bf16_f32 v75, v92, v93
	global_store_dwordx4 v[76:77], v[72:75], off offset:2560 nt

;     __device__ __forceinline__ void operator()(Acc& acc, const Unit& u, int wr, int wc, int fr, int fq) const {
;     ...
;                 if (gate_tile) {
;                     if (wc == 0 && fq == 0) { *(f32x4*)(gates + (size_t)row * 8) = acc[ai][0][m][0] * r; *(f32x4*)(gates + (size_t)row * 8 + 4) = acc[ai][0][m][1] * r; }
.LBB0_913:
	s_andn2_b64 vcc, exec, s[26:27]
	s_cbranch_vccnz .LBB0_917
	s_and_saveexec_b64 s[26:27], s[2:3]
	s_cbranch_execz .LBB0_916
	v_ashrrev_i32_e32 v83, 31, v82
	v_lshlrev_b64 v[72:73], 5, v[82:83]
	v_lshl_add_u64 v[72:73], s[12:13], 0, v[72:73]
	s_waitcnt lgkmcnt(0)
	v_pk_mul_f32 v[70:71], v[70:71], v[80:81] op_sel_hi:[1,0]
	v_pk_mul_f32 v[68:69], v[68:69], v[80:81] op_sel_hi:[1,0]
	v_pk_mul_f32 v[66:67], v[66:67], v[80:81] op_sel_hi:[1,0]
	v_pk_mul_f32 v[64:65], v[64:65], v[80:81] op_sel_hi:[1,0]
	global_store_dwordx4 v[72:73], v[68:71], off nt
	global_store_dwordx4 v[72:73], v[64:67], off offset:16 nt

;     __device__ __forceinline__ void operator()(Acc& acc, const Unit& u, int wr, int wc, int fr, int fq) const {
;     ...
;             for (int m = 0; m < 4; ++m) {
;                 const int row = row0 + ai * HALF + m * 16;
;                 const float r = rs[u.idx * BM + wr * 64 + fr + ai * HALF + m * 16];
;                 if (gate_tile) {
;                     if (wc == 0 && fq == 0) { *(f32x4*)(gates + (size_t)row * 8) = acc[ai][0][m][0] * r; *(f32x4*)(gates + (size_t)row * 8 + 4) = acc[ai][0][m][1] * r; }
;                 } else if (u.pn >= 9) {
;                     const float c1 = -r * 1.4426950408889634f;
;                     f32x4 R[2], S[2];
; #pragma unroll
;                     for (int n = 0; n < 2; ++n) {
;                         const f32x4 tm = acc[ai][0][m][n] * c1, ta = acc[ai][1][m][n] * c1; f32x4 em, ea;
; #pragma unroll
;                         for (int i = 0; i < 4; ++i) { em[i] = __builtin_amdgcn_exp2f(tm[i]); ea[i] = __builtin_amdgcn_exp2f(ta[i]); }
;                         const f32x4 dm = em + 1.0f, da = ea + 1.0f; f32x4 qm, qa;
; #pragma unroll
;                         for (int i = 0; i < 4; ++i) { qm[i] = __builtin_amdgcn_rcpf(dm[i]); qa[i] = __builtin_amdgcn_rcpf(da[i]); }
;                         R[n] = da * qm; S[n] = qa;
;                     }
;                     const int gcol = (u.pn - 9) * HALF + wc * 32 + 8 * fq;
;                     u32x4 w; w.x = cvt_pk_bf16(R[0][0], R[0][1]); w.y = cvt_pk_bf16(R[0][2], R[0][3]); w.z = cvt_pk_bf16(R[1][0], R[1][1]); w.w = cvt_pk_bf16(R[1][2], R[1][3]);
;                     *(u32x4*)(P + (size_t)row * NIN + PC_GM + gcol) = w;
;                     w.x = cvt_pk_bf16(S[0][0], S[0][1]); w.y = cvt_pk_bf16(S[0][2], S[0][3]); w.z = cvt_pk_bf16(S[1][0], S[1][1]); w.w = cvt_pk_bf16(S[1][2], S[1][3]);
;                     *(u32x4*)(P + (size_t)row * NIN + PC_GA + gcol) = w;
;                 } else {
; #pragma unroll
;                     for (int bj = 0; bj < 2; ++bj) {
;                         const f32x4 v0 = acc[ai][bj][m][0] * r, v1 = acc[ai][bj][m][1] * r;
;                         u32x4 w; w.x = cvt_pk_bf16(v0[0], v0[1]); w.y = cvt_pk_bf16(v0[2], v0[3]); w.z = cvt_pk_bf16(v1[0], v1[1]); w.w = cvt_pk_bf16(v1[2], v1[3]);
;                         *(u32x4*)(P + (size_t)row * NIN + col0 + bj * HALF) = w;
;                     }
.LBB0_917:
	ds_read_b32 v64, v161 offset:512
	v_add_u32_e32 v66, 0x80, v148
	s_and_b64 vcc, exec, s[6:7]
	s_mov_b64 s[26:27], -1
	s_cbranch_vccnz .LBB0_923
	s_cmp_gt_i32 s8, 8
	s_cbranch_scc1 .LBB0_920
	s_waitcnt lgkmcnt(0)
	v_pk_mul_f32 v[70:71], v[54:55], v[64:65] op_sel_hi:[1,0]
	v_pk_mul_f32 v[68:69], v[52:53], v[64:65] op_sel_hi:[1,0]
	v_pk_mul_f32 v[72:73], v[50:51], v[64:65] op_sel_hi:[1,0]
	v_pk_mul_f32 v[74:75], v[48:49], v[64:65] op_sel_hi:[1,0]
	v_cvt_pk_bf16_f32 v68, v68, v69
	v_cvt_pk_bf16_f32 v69, v70, v71
	v_pk_mul_f32 v[76:77], v[56:57], v[64:65] op_sel_hi:[1,0]
	v_cvt_pk_bf16_f32 v70, v74, v75
	v_cvt_pk_bf16_f32 v71, v72, v73
	v_mov_b64_e32 v[72:73], s[68:69]
	v_mad_i64_i32 v[72:73], s[26:27], v66, s47, v[72:73]
	v_lshl_add_u64 v[72:73], v[146:147], 1, v[72:73]
	global_store_dwordx4 v[72:73], v[68:71], off nt
	s_mov_b64 s[26:27], 0
	v_pk_mul_f32 v[74:75], v[58:59], v[64:65] op_sel_hi:[1,0]
	v_pk_mul_f32 v[70:71], v[62:63], v[64:65] op_sel_hi:[1,0]
	v_pk_mul_f32 v[68:69], v[60:61], v[64:65] op_sel_hi:[1,0]
	s_nop 0
	v_cvt_pk_bf16_f32 v68, v68, v69
	v_cvt_pk_bf16_f32 v69, v70, v71
	v_cvt_pk_bf16_f32 v70, v76, v77
	v_cvt_pk_bf16_f32 v71, v74, v75
	global_store_dwordx4 v[72:73], v[68:71], off offset:256 nt
.LBB0_920:
	s_andn2_b64 vcc, exec, s[26:27]
	s_cbranch_vccnz .LBB0_922
	s_waitcnt lgkmcnt(0)
	v_mul_f32_e32 v65, 0xbfb8aa3b, v64
	v_mul_f32_e32 v68, v53, v65
	v_exp_f32_e32 v69, v68
	v_mul_f32_e32 v68, v54, v65
	v_mul_f32_e32 v67, v52, v65
	v_exp_f32_e32 v70, v68
	v_mul_f32_e32 v68, v55, v65
	v_exp_f32_e32 v67, v67
	v_exp_f32_e32 v71, v68
	v_mul_f32_e32 v60, v60, v65
	v_mul_f32_e32 v61, v61, v65
	v_mul_f32_e32 v62, v62, v65
	v_mul_f32_e32 v63, v63, v65
	v_exp_f32_e32 v60, v60
	v_exp_f32_e32 v61, v61
	v_exp_f32_e32 v62, v62
	v_exp_f32_e32 v63, v63
	v_add_f32_e32 v67, 1.0, v67
	v_add_f32_e32 v69, 1.0, v69
	v_add_f32_e32 v70, 1.0, v70
	v_add_f32_e32 v71, 1.0, v71
	v_rcp_f32_e32 v68, v67
	v_rcp_f32_e32 v69, v69
	v_rcp_f32_e32 v70, v70
	v_rcp_f32_e32 v71, v71
	v_pk_add_f32 v[62:63], v[62:63], 1.0 op_sel_hi:[1,0]
	v_pk_add_f32 v[60:61], v[60:61], 1.0 op_sel_hi:[1,0]
	v_rcp_f32_e32 v73, v62
	v_rcp_f32_e32 v67, v60
	v_rcp_f32_e32 v72, v61
	v_rcp_f32_e32 v74, v63
	v_pk_mul_f32 v[62:63], v[62:63], v[70:71]
	v_pk_mul_f32 v[60:61], v[60:61], v[68:69]
	v_mul_f32_e32 v68, v48, v65
	v_mul_f32_e32 v56, v56, v65
	v_mul_f32_e32 v69, v49, v65
	v_mul_f32_e32 v57, v57, v65
	v_mul_f32_e32 v70, v50, v65
	v_mul_f32_e32 v58, v58, v65
	v_mul_f32_e32 v59, v59, v65
	v_mul_f32_e32 v65, v51, v65
	v_exp_f32_e32 v68, v68
	v_exp_f32_e32 v69, v69
	v_exp_f32_e32 v70, v70
	v_exp_f32_e32 v65, v65
	v_exp_f32_e32 v56, v56
	v_exp_f32_e32 v57, v57
	v_exp_f32_e32 v58, v58
	v_exp_f32_e32 v59, v59
	v_add_f32_e32 v68, 1.0, v68
	v_add_f32_e32 v69, 1.0, v69
	v_add_f32_e32 v70, 1.0, v70
	v_add_f32_e32 v65, 1.0, v65
	v_rcp_f32_e32 v68, v68
	v_rcp_f32_e32 v69, v69
	v_rcp_f32_e32 v70, v70
	v_rcp_f32_e32 v71, v65
	v_pk_add_f32 v[58:59], v[58:59], 1.0 op_sel_hi:[1,0]
	v_pk_add_f32 v[56:57], v[56:57], 1.0 op_sel_hi:[1,0]
	v_rcp_f32_e32 v76, v58
	v_rcp_f32_e32 v75, v56
	v_rcp_f32_e32 v77, v59
	v_pk_mul_f32 v[70:71], v[58:59], v[70:71]
	v_pk_mul_f32 v[58:59], v[56:57], v[68:69]
	v_cvt_pk_bf16_f32 v56, v60, v61
	v_mov_b64_e32 v[60:61], s[68:69]
	v_lshl_add_u32 v136, s8, 7, v156
	v_mad_i64_i32 v[60:61], s[26:27], v66, s47, v[60:61]
	v_lshl_add_u64 v[60:61], v[136:137], 1, v[60:61]
	v_add_co_u32_e32 v60, vcc, 0x1000, v60
	v_rcp_f32_e32 v65, v57
	v_cvt_pk_bf16_f32 v57, v62, v63
	v_cvt_pk_bf16_f32 v58, v58, v59
	v_cvt_pk_bf16_f32 v59, v70, v71
	s_nop 0
	v_addc_co_u32_e32 v61, vcc, 0, v61, vcc
	global_store_dwordx4 v[60:61], v[56:59], off offset:512 nt
	s_nop 1
	v_cvt_pk_bf16_f32 v56, v67, v72
	v_cvt_pk_bf16_f32 v57, v73, v74
	v_cvt_pk_bf16_f32 v58, v75, v65
	v_cvt_pk_bf16_f32 v59, v76, v77
	global_store_dwordx4 v[60:61], v[56:59], off offset:2560 nt

;     __device__ __forceinline__ void operator()(Acc& acc, const Unit& u, int wr, int wc, int fr, int fq) const {
;     ...
;                 if (gate_tile) {
;                     if (wc == 0 && fq == 0) { *(f32x4*)(gates + (size_t)row * 8) = acc[ai][0][m][0] * r; *(f32x4*)(gates + (size_t)row * 8 + 4) = acc[ai][0][m][1] * r; }
.LBB0_923:
	s_andn2_b64 vcc, exec, s[26:27]
	s_cbranch_vccnz .LBB0_927
	s_and_saveexec_b64 s[26:27], s[2:3]
	s_cbranch_execz .LBB0_926
	v_ashrrev_i32_e32 v67, 31, v66
	v_lshlrev_b64 v[56:57], 5, v[66:67]
	v_lshl_add_u64 v[56:57], s[12:13], 0, v[56:57]
	s_waitcnt lgkmcnt(0)
	v_pk_mul_f32 v[54:55], v[54:55], v[64:65] op_sel_hi:[1,0]
	v_pk_mul_f32 v[52:53], v[52:53], v[64:65] op_sel_hi:[1,0]
	v_pk_mul_f32 v[50:51], v[50:51], v[64:65] op_sel_hi:[1,0]
	v_pk_mul_f32 v[48:49], v[48:49], v[64:65] op_sel_hi:[1,0]
	global_store_dwordx4 v[56:57], v[52:55], off nt
	global_store_dwordx4 v[56:57], v[48:51], off offset:16 nt

;     __device__ __forceinline__ void operator()(Acc& acc, const Unit& u, int wr, int wc, int fr, int fq) const {
;     ...
;             for (int m = 0; m < 4; ++m) {
;                 const int row = row0 + ai * HALF + m * 16;
;                 const float r = rs[u.idx * BM + wr * 64 + fr + ai * HALF + m * 16];
;                 if (gate_tile) {
;                     if (wc == 0 && fq == 0) { *(f32x4*)(gates + (size_t)row * 8) = acc[ai][0][m][0] * r; *(f32x4*)(gates + (size_t)row * 8 + 4) = acc[ai][0][m][1] * r; }
;                 } else if (u.pn >= 9) {
;                     const float c1 = -r * 1.4426950408889634f;
;                     f32x4 R[2], S[2];
; #pragma unroll
;                     for (int n = 0; n < 2; ++n) {
;                         const f32x4 tm = acc[ai][0][m][n] * c1, ta = acc[ai][1][m][n] * c1; f32x4 em, ea;
; #pragma unroll
;                         for (int i = 0; i < 4; ++i) { em[i] = __builtin_amdgcn_exp2f(tm[i]); ea[i] = __builtin_amdgcn_exp2f(ta[i]); }
;                         const f32x4 dm = em + 1.0f, da = ea + 1.0f; f32x4 qm, qa;
; #pragma unroll
;                         for (int i = 0; i < 4; ++i) { qm[i] = __builtin_amdgcn_rcpf(dm[i]); qa[i] = __builtin_amdgcn_rcpf(da[i]); }
;                         R[n] = da * qm; S[n] = qa;
;                     }
;                     const int gcol = (u.pn - 9) * HALF + wc * 32 + 8 * fq;
;                     u32x4 w; w.x = cvt_pk_bf16(R[0][0], R[0][1]); w.y = cvt_pk_bf16(R[0][2], R[0][3]); w.z = cvt_pk_bf16(R[1][0], R[1][1]); w.w = cvt_pk_bf16(R[1][2], R[1][3]);
;                     *(u32x4*)(P + (size_t)row * NIN + PC_GM + gcol) = w;
;                     w.x = cvt_pk_bf16(S[0][0], S[0][1]); w.y = cvt_pk_bf16(S[0][2], S[0][3]); w.z = cvt_pk_bf16(S[1][0], S[1][1]); w.w = cvt_pk_bf16(S[1][2], S[1][3]);
;                     *(u32x4*)(P + (size_t)row * NIN + PC_GA + gcol) = w;
;                 } else {
; #pragma unroll
;                     for (int bj = 0; bj < 2; ++bj) {
;                         const f32x4 v0 = acc[ai][bj][m][0] * r, v1 = acc[ai][bj][m][1] * r;
;                         u32x4 w; w.x = cvt_pk_bf16(v0[0], v0[1]); w.y = cvt_pk_bf16(v0[2], v0[3]); w.z = cvt_pk_bf16(v1[0], v1[1]); w.w = cvt_pk_bf16(v1[2], v1[3]);
;                         *(u32x4*)(P + (size_t)row * NIN + col0 + bj * HALF) = w;
;                     }
.LBB0_927:
	ds_read_b32 v48, v161 offset:576
	v_add_u32_e32 v50, 0x90, v148
	s_and_b64 vcc, exec, s[6:7]
	s_mov_b64 s[26:27], -1
	s_cbranch_vccnz .LBB0_933
	s_cmp_gt_i32 s8, 8
	s_cbranch_scc1 .LBB0_930
	s_waitcnt lgkmcnt(0)
	v_pk_mul_f32 v[54:55], v[38:39], v[48:49] op_sel_hi:[1,0]
	v_pk_mul_f32 v[52:53], v[36:37], v[48:49] op_sel_hi:[1,0]
	v_pk_mul_f32 v[56:57], v[34:35], v[48:49] op_sel_hi:[1,0]
	v_pk_mul_f32 v[58:59], v[32:33], v[48:49] op_sel_hi:[1,0]
	v_cvt_pk_bf16_f32 v52, v52, v53
	v_cvt_pk_bf16_f32 v53, v54, v55
	v_pk_mul_f32 v[60:61], v[40:41], v[48:49] op_sel_hi:[1,0]
	v_cvt_pk_bf16_f32 v54, v58, v59
	v_cvt_pk_bf16_f32 v55, v56, v57
	v_mov_b64_e32 v[56:57], s[68:69]
	v_mad_i64_i32 v[56:57], s[26:27], v50, s47, v[56:57]
	v_lshl_add_u64 v[56:57], v[146:147], 1, v[56:57]
	global_store_dwordx4 v[56:57], v[52:55], off nt
	s_mov_b64 s[26:27], 0
	v_pk_mul_f32 v[58:59], v[42:43], v[48:49] op_sel_hi:[1,0]
	v_pk_mul_f32 v[54:55], v[46:47], v[48:49] op_sel_hi:[1,0]
	v_pk_mul_f32 v[52:53], v[44:45], v[48:49] op_sel_hi:[1,0]
	s_nop 0
	v_cvt_pk_bf16_f32 v52, v52, v53
	v_cvt_pk_bf16_f32 v53, v54, v55
	v_cvt_pk_bf16_f32 v54, v60, v61
	v_cvt_pk_bf16_f32 v55, v58, v59
	global_store_dwordx4 v[56:57], v[52:55], off offset:256 nt
.LBB0_930:
	s_andn2_b64 vcc, exec, s[26:27]
	s_cbranch_vccnz .LBB0_932
	s_waitcnt lgkmcnt(0)
	v_mul_f32_e32 v49, 0xbfb8aa3b, v48
	v_mul_f32_e32 v52, v37, v49
	v_exp_f32_e32 v53, v52
	v_mul_f32_e32 v52, v38, v49
	v_mul_f32_e32 v51, v36, v49
	v_exp_f32_e32 v54, v52
	v_mul_f32_e32 v52, v39, v49
	v_exp_f32_e32 v51, v51
	v_exp_f32_e32 v55, v52
	v_mul_f32_e32 v44, v44, v49
	v_mul_f32_e32 v45, v45, v49
	v_mul_f32_e32 v46, v46, v49
	v_mul_f32_e32 v47, v47, v49
	v_exp_f32_e32 v44, v44
	v_exp_f32_e32 v45, v45
	v_exp_f32_e32 v46, v46
	v_exp_f32_e32 v47, v47
	v_add_f32_e32 v51, 1.0, v51
	v_add_f32_e32 v53, 1.0, v53
	v_add_f32_e32 v54, 1.0, v54
	v_add_f32_e32 v55, 1.0, v55
	v_rcp_f32_e32 v52, v51
	v_rcp_f32_e32 v53, v53
	v_rcp_f32_e32 v54, v54
	v_rcp_f32_e32 v55, v55
	v_pk_add_f32 v[46:47], v[46:47], 1.0 op_sel_hi:[1,0]
	v_pk_add_f32 v[44:45], v[44:45], 1.0 op_sel_hi:[1,0]
	v_rcp_f32_e32 v57, v46
	v_rcp_f32_e32 v51, v44
	v_rcp_f32_e32 v56, v45
	v_rcp_f32_e32 v58, v47
	v_pk_mul_f32 v[46:47], v[46:47], v[54:55]
	v_pk_mul_f32 v[44:45], v[44:45], v[52:53]
	v_mul_f32_e32 v52, v32, v49
	v_mul_f32_e32 v40, v40, v49
	v_mul_f32_e32 v53, v33, v49
	v_mul_f32_e32 v41, v41, v49
	v_mul_f32_e32 v54, v34, v49
	v_mul_f32_e32 v42, v42, v49
	v_mul_f32_e32 v43, v43, v49
	v_mul_f32_e32 v49, v35, v49
	v_exp_f32_e32 v52, v52
	v_exp_f32_e32 v53, v53
	v_exp_f32_e32 v54, v54
	v_exp_f32_e32 v49, v49
	v_exp_f32_e32 v40, v40
	v_exp_f32_e32 v41, v41
	v_exp_f32_e32 v42, v42
	v_exp_f32_e32 v43, v43
	v_add_f32_e32 v52, 1.0, v52
	v_add_f32_e32 v53, 1.0, v53
	v_add_f32_e32 v54, 1.0, v54
	v_add_f32_e32 v49, 1.0, v49
	v_rcp_f32_e32 v52, v52
	v_rcp_f32_e32 v53, v53
	v_rcp_f32_e32 v54, v54
	v_rcp_f32_e32 v55, v49
	v_pk_add_f32 v[42:43], v[42:43], 1.0 op_sel_hi:[1,0]
	v_pk_add_f32 v[40:41], v[40:41], 1.0 op_sel_hi:[1,0]
	v_rcp_f32_e32 v60, v42
	v_rcp_f32_e32 v59, v40
	v_rcp_f32_e32 v61, v43
	v_pk_mul_f32 v[54:55], v[42:43], v[54:55]
	v_pk_mul_f32 v[42:43], v[40:41], v[52:53]
	v_cvt_pk_bf16_f32 v40, v44, v45
	v_mov_b64_e32 v[44:45], s[68:69]
	v_lshl_add_u32 v136, s8, 7, v156
	v_mad_i64_i32 v[44:45], s[26:27], v50, s47, v[44:45]
	v_lshl_add_u64 v[44:45], v[136:137], 1, v[44:45]
	v_add_co_u32_e32 v44, vcc, 0x1000, v44
	v_rcp_f32_e32 v49, v41
	v_cvt_pk_bf16_f32 v41, v46, v47
	v_cvt_pk_bf16_f32 v42, v42, v43
	v_cvt_pk_bf16_f32 v43, v54, v55
	s_nop 0
	v_addc_co_u32_e32 v45, vcc, 0, v45, vcc
	global_store_dwordx4 v[44:45], v[40:43], off offset:512 nt
	s_nop 1
	v_cvt_pk_bf16_f32 v40, v51, v56
	v_cvt_pk_bf16_f32 v41, v57, v58
	v_cvt_pk_bf16_f32 v42, v59, v49
	v_cvt_pk_bf16_f32 v43, v60, v61
	global_store_dwordx4 v[44:45], v[40:43], off offset:2560 nt

;     __device__ __forceinline__ void operator()(Acc& acc, const Unit& u, int wr, int wc, int fr, int fq) const {
;     ...
;                 if (gate_tile) {
;                     if (wc == 0 && fq == 0) { *(f32x4*)(gates + (size_t)row * 8) = acc[ai][0][m][0] * r; *(f32x4*)(gates + (size_t)row * 8 + 4) = acc[ai][0][m][1] * r; }
.LBB0_933:
	s_andn2_b64 vcc, exec, s[26:27]
	s_cbranch_vccnz .LBB0_937
	s_and_saveexec_b64 s[26:27], s[2:3]
	s_cbranch_execz .LBB0_936
	v_ashrrev_i32_e32 v51, 31, v50
	v_lshlrev_b64 v[40:41], 5, v[50:51]
	v_lshl_add_u64 v[40:41], s[12:13], 0, v[40:41]
	s_waitcnt lgkmcnt(0)
	v_pk_mul_f32 v[38:39], v[38:39], v[48:49] op_sel_hi:[1,0]
	v_pk_mul_f32 v[36:37], v[36:37], v[48:49] op_sel_hi:[1,0]
	v_pk_mul_f32 v[34:35], v[34:35], v[48:49] op_sel_hi:[1,0]
	v_pk_mul_f32 v[32:33], v[32:33], v[48:49] op_sel_hi:[1,0]
	global_store_dwordx4 v[40:41], v[36:39], off nt
	global_store_dwordx4 v[40:41], v[32:35], off offset:16 nt

;     __device__ __forceinline__ void operator()(Acc& acc, const Unit& u, int wr, int wc, int fr, int fq) const {
;     ...
;             for (int m = 0; m < 4; ++m) {
;                 const int row = row0 + ai * HALF + m * 16;
;                 const float r = rs[u.idx * BM + wr * 64 + fr + ai * HALF + m * 16];
;                 if (gate_tile) {
;                     if (wc == 0 && fq == 0) { *(f32x4*)(gates + (size_t)row * 8) = acc[ai][0][m][0] * r; *(f32x4*)(gates + (size_t)row * 8 + 4) = acc[ai][0][m][1] * r; }
;                 } else if (u.pn >= 9) {
;                     const float c1 = -r * 1.4426950408889634f;
;                     f32x4 R[2], S[2];
; #pragma unroll
;                     for (int n = 0; n < 2; ++n) {
;                         const f32x4 tm = acc[ai][0][m][n] * c1, ta = acc[ai][1][m][n] * c1; f32x4 em, ea;
; #pragma unroll
;                         for (int i = 0; i < 4; ++i) { em[i] = __builtin_amdgcn_exp2f(tm[i]); ea[i] = __builtin_amdgcn_exp2f(ta[i]); }
;                         const f32x4 dm = em + 1.0f, da = ea + 1.0f; f32x4 qm, qa;
; #pragma unroll
;                         for (int i = 0; i < 4; ++i) { qm[i] = __builtin_amdgcn_rcpf(dm[i]); qa[i] = __builtin_amdgcn_rcpf(da[i]); }
;                         R[n] = da * qm; S[n] = qa;
;                     }
;                     const int gcol = (u.pn - 9) * HALF + wc * 32 + 8 * fq;
;                     u32x4 w; w.x = cvt_pk_bf16(R[0][0], R[0][1]); w.y = cvt_pk_bf16(R[0][2], R[0][3]); w.z = cvt_pk_bf16(R[1][0], R[1][1]); w.w = cvt_pk_bf16(R[1][2], R[1][3]);
;                     *(u32x4*)(P + (size_t)row * NIN + PC_GM + gcol) = w;
;                     w.x = cvt_pk_bf16(S[0][0], S[0][1]); w.y = cvt_pk_bf16(S[0][2], S[0][3]); w.z = cvt_pk_bf16(S[1][0], S[1][1]); w.w = cvt_pk_bf16(S[1][2], S[1][3]);
;                     *(u32x4*)(P + (size_t)row * NIN + PC_GA + gcol) = w;
;                 } else {
; #pragma unroll
;                     for (int bj = 0; bj < 2; ++bj) {
;                         const f32x4 v0 = acc[ai][bj][m][0] * r, v1 = acc[ai][bj][m][1] * r;
;                         u32x4 w; w.x = cvt_pk_bf16(v0[0], v0[1]); w.y = cvt_pk_bf16(v0[2], v0[3]); w.z = cvt_pk_bf16(v1[0], v1[1]); w.w = cvt_pk_bf16(v1[2], v1[3]);
;                         *(u32x4*)(P + (size_t)row * NIN + col0 + bj * HALF) = w;
;                     }
.LBB0_937:
	ds_read_b32 v32, v161 offset:640
	v_add_u32_e32 v34, 0xa0, v148
	s_and_b64 vcc, exec, s[6:7]
	s_mov_b64 s[26:27], -1
	s_cbranch_vccnz .LBB0_943
	s_cmp_gt_i32 s8, 8
	s_cbranch_scc1 .LBB0_940
	s_waitcnt lgkmcnt(0)
	v_pk_mul_f32 v[38:39], v[22:23], v[32:33] op_sel_hi:[1,0]
	v_pk_mul_f32 v[36:37], v[20:21], v[32:33] op_sel_hi:[1,0]
	v_pk_mul_f32 v[40:41], v[18:19], v[32:33] op_sel_hi:[1,0]
	v_pk_mul_f32 v[42:43], v[16:17], v[32:33] op_sel_hi:[1,0]
	v_cvt_pk_bf16_f32 v36, v36, v37
	v_cvt_pk_bf16_f32 v37, v38, v39
	v_pk_mul_f32 v[44:45], v[24:25], v[32:33] op_sel_hi:[1,0]
	v_cvt_pk_bf16_f32 v38, v42, v43
	v_cvt_pk_bf16_f32 v39, v40, v41
	v_mov_b64_e32 v[40:41], s[68:69]
	v_mad_i64_i32 v[40:41], s[26:27], v34, s47, v[40:41]
	v_lshl_add_u64 v[40:41], v[146:147], 1, v[40:41]
	global_store_dwordx4 v[40:41], v[36:39], off nt
	s_mov_b64 s[26:27], 0
	v_pk_mul_f32 v[42:43], v[26:27], v[32:33] op_sel_hi:[1,0]
	v_pk_mul_f32 v[38:39], v[30:31], v[32:33] op_sel_hi:[1,0]
	v_pk_mul_f32 v[36:37], v[28:29], v[32:33] op_sel_hi:[1,0]
	s_nop 0
	v_cvt_pk_bf16_f32 v36, v36, v37
	v_cvt_pk_bf16_f32 v37, v38, v39
	v_cvt_pk_bf16_f32 v38, v44, v45
	v_cvt_pk_bf16_f32 v39, v42, v43
	global_store_dwordx4 v[40:41], v[36:39], off offset:256 nt
.LBB0_940:
	s_andn2_b64 vcc, exec, s[26:27]
	s_cbranch_vccnz .LBB0_942
	s_waitcnt lgkmcnt(0)
	v_mul_f32_e32 v33, 0xbfb8aa3b, v32
	v_mul_f32_e32 v36, v21, v33
	v_exp_f32_e32 v37, v36
	v_mul_f32_e32 v36, v22, v33
	v_mul_f32_e32 v35, v20, v33
	v_exp_f32_e32 v38, v36
	v_mul_f32_e32 v36, v23, v33
	v_exp_f32_e32 v35, v35
	v_exp_f32_e32 v39, v36
	v_mul_f32_e32 v28, v28, v33
	v_mul_f32_e32 v29, v29, v33
	v_mul_f32_e32 v30, v30, v33
	v_mul_f32_e32 v31, v31, v33
	v_exp_f32_e32 v28, v28
	v_exp_f32_e32 v29, v29
	v_exp_f32_e32 v30, v30
	v_exp_f32_e32 v31, v31
	v_add_f32_e32 v35, 1.0, v35
	v_add_f32_e32 v37, 1.0, v37
	v_add_f32_e32 v38, 1.0, v38
	v_add_f32_e32 v39, 1.0, v39
	v_rcp_f32_e32 v36, v35
	v_rcp_f32_e32 v37, v37
	v_rcp_f32_e32 v38, v38
	v_rcp_f32_e32 v39, v39
	v_pk_add_f32 v[30:31], v[30:31], 1.0 op_sel_hi:[1,0]
	v_pk_add_f32 v[28:29], v[28:29], 1.0 op_sel_hi:[1,0]
	v_rcp_f32_e32 v41, v30
	v_rcp_f32_e32 v35, v28
	v_rcp_f32_e32 v40, v29
	v_rcp_f32_e32 v42, v31
	v_pk_mul_f32 v[30:31], v[30:31], v[38:39]
	v_pk_mul_f32 v[28:29], v[28:29], v[36:37]
	v_mul_f32_e32 v36, v16, v33
	v_mul_f32_e32 v24, v24, v33
	v_mul_f32_e32 v37, v17, v33
	v_mul_f32_e32 v25, v25, v33
	v_mul_f32_e32 v38, v18, v33
	v_mul_f32_e32 v26, v26, v33
	v_mul_f32_e32 v27, v27, v33
	v_mul_f32_e32 v33, v19, v33
	v_exp_f32_e32 v36, v36
	v_exp_f32_e32 v37, v37
	v_exp_f32_e32 v38, v38
	v_exp_f32_e32 v33, v33
	v_exp_f32_e32 v24, v24
	v_exp_f32_e32 v25, v25
	v_exp_f32_e32 v26, v26
	v_exp_f32_e32 v27, v27
	v_add_f32_e32 v36, 1.0, v36
	v_add_f32_e32 v37, 1.0, v37
	v_add_f32_e32 v38, 1.0, v38
	v_add_f32_e32 v33, 1.0, v33
	v_rcp_f32_e32 v36, v36
	v_rcp_f32_e32 v37, v37
	v_rcp_f32_e32 v38, v38
	v_rcp_f32_e32 v39, v33
	v_pk_add_f32 v[26:27], v[26:27], 1.0 op_sel_hi:[1,0]
	v_pk_add_f32 v[24:25], v[24:25], 1.0 op_sel_hi:[1,0]
	v_rcp_f32_e32 v44, v26
	v_rcp_f32_e32 v43, v24
	v_rcp_f32_e32 v45, v27
	v_pk_mul_f32 v[38:39], v[26:27], v[38:39]
	v_pk_mul_f32 v[26:27], v[24:25], v[36:37]
	v_cvt_pk_bf16_f32 v24, v28, v29
	v_mov_b64_e32 v[28:29], s[68:69]
	v_lshl_add_u32 v136, s8, 7, v156
	v_mad_i64_i32 v[28:29], s[26:27], v34, s47, v[28:29]
	v_lshl_add_u64 v[28:29], v[136:137], 1, v[28:29]
	v_add_co_u32_e32 v28, vcc, 0x1000, v28
	v_rcp_f32_e32 v33, v25
	v_cvt_pk_bf16_f32 v25, v30, v31
	v_cvt_pk_bf16_f32 v26, v26, v27
	v_cvt_pk_bf16_f32 v27, v38, v39
	s_nop 0
	v_addc_co_u32_e32 v29, vcc, 0, v29, vcc
	global_store_dwordx4 v[28:29], v[24:27], off offset:512 nt
	s_nop 1
	v_cvt_pk_bf16_f32 v24, v35, v40
	v_cvt_pk_bf16_f32 v25, v41, v42
	v_cvt_pk_bf16_f32 v26, v43, v33
	v_cvt_pk_bf16_f32 v27, v44, v45
	global_store_dwordx4 v[28:29], v[24:27], off offset:2560 nt

;     __device__ __forceinline__ void operator()(Acc& acc, const Unit& u, int wr, int wc, int fr, int fq) const {
;     ...
;                 if (gate_tile) {
;                     if (wc == 0 && fq == 0) { *(f32x4*)(gates + (size_t)row * 8) = acc[ai][0][m][0] * r; *(f32x4*)(gates + (size_t)row * 8 + 4) = acc[ai][0][m][1] * r; }
.LBB0_943:
	s_andn2_b64 vcc, exec, s[26:27]
	s_cbranch_vccnz .LBB0_947
	s_and_saveexec_b64 s[26:27], s[2:3]
	s_cbranch_execz .LBB0_946
	v_ashrrev_i32_e32 v35, 31, v34
	v_lshlrev_b64 v[24:25], 5, v[34:35]
	v_lshl_add_u64 v[24:25], s[12:13], 0, v[24:25]
	s_waitcnt lgkmcnt(0)
	v_pk_mul_f32 v[22:23], v[22:23], v[32:33] op_sel_hi:[1,0]
	v_pk_mul_f32 v[20:21], v[20:21], v[32:33] op_sel_hi:[1,0]
	v_pk_mul_f32 v[18:19], v[18:19], v[32:33] op_sel_hi:[1,0]
	v_pk_mul_f32 v[16:17], v[16:17], v[32:33] op_sel_hi:[1,0]
	global_store_dwordx4 v[24:25], v[20:23], off nt
	global_store_dwordx4 v[24:25], v[16:19], off offset:16 nt

; __device__ __forceinline__ unsigned cvt_pk_bf16(float lo, float hi) { unsigned r; asm volatile("v_cvt_pk_bf16_f32 %0, %1, %2" : "=v"(r) : "v"(lo), "v"(hi)); return r; }
;     __device__ __forceinline__ void operator()(Acc& acc, const Unit& u, int wr, int wc, int fr, int fq) const {
;     ...
;                 } else if (u.pn >= 9) {
;                     const float c1 = -r * 1.4426950408889634f;
;                     f32x4 R[2], S[2];
; #pragma unroll
;                     for (int n = 0; n < 2; ++n) {
;                         const f32x4 tm = acc[ai][0][m][n] * c1, ta = acc[ai][1][m][n] * c1; f32x4 em, ea;
; #pragma unroll
;                         for (int i = 0; i < 4; ++i) { em[i] = __builtin_amdgcn_exp2f(tm[i]); ea[i] = __builtin_amdgcn_exp2f(ta[i]); }
;                         const f32x4 dm = em + 1.0f, da = ea + 1.0f; f32x4 qm, qa;
; #pragma unroll
;                         for (int i = 0; i < 4; ++i) { qm[i] = __builtin_amdgcn_rcpf(dm[i]); qa[i] = __builtin_amdgcn_rcpf(da[i]); }
;                         R[n] = da * qm; S[n] = qa;
;                     }
;                     const int gcol = (u.pn - 9) * HALF + wc * 32 + 8 * fq;
;                     u32x4 w; w.x = cvt_pk_bf16(R[0][0], R[0][1]); w.y = cvt_pk_bf16(R[0][2], R[0][3]); w.z = cvt_pk_bf16(R[1][0], R[1][1]); w.w = cvt_pk_bf16(R[1][2], R[1][3]);
;                     *(u32x4*)(P + (size_t)row * NIN + PC_GM + gcol) = w;
;                     w.x = cvt_pk_bf16(S[0][0], S[0][1]); w.y = cvt_pk_bf16(S[0][2], S[0][3]); w.z = cvt_pk_bf16(S[1][0], S[1][1]); w.w = cvt_pk_bf16(S[1][2], S[1][3]);
;                     *(u32x4*)(P + (size_t)row * NIN + PC_GA + gcol) = w;
;                 } else {
; #pragma unroll
;                     for (int bj = 0; bj < 2; ++bj) {
;                         const f32x4 v0 = acc[ai][bj][m][0] * r, v1 = acc[ai][bj][m][1] * r;
;                         u32x4 w; w.x = cvt_pk_bf16(v0[0], v0[1]); w.y = cvt_pk_bf16(v0[2], v0[3]); w.z = cvt_pk_bf16(v1[0], v1[1]); w.w = cvt_pk_bf16(v1[2], v1[3]);
;                         *(u32x4*)(P + (size_t)row * NIN + col0 + bj * HALF) = w;
;                     }
.LBB0_950:
	s_cmp_gt_i32 s8, 8
	s_cbranch_scc1 .LBB0_952
	s_waitcnt lgkmcnt(0)
	v_pk_mul_f32 v[22:23], v[6:7], v[16:17] op_sel_hi:[1,0]
	v_pk_mul_f32 v[20:21], v[4:5], v[16:17] op_sel_hi:[1,0]
	v_pk_mul_f32 v[24:25], v[2:3], v[16:17] op_sel_hi:[1,0]
	v_pk_mul_f32 v[26:27], v[0:1], v[16:17] op_sel_hi:[1,0]
	v_cvt_pk_bf16_f32 v20, v20, v21
	v_cvt_pk_bf16_f32 v21, v22, v23
	v_pk_mul_f32 v[28:29], v[8:9], v[16:17] op_sel_hi:[1,0]
	v_cvt_pk_bf16_f32 v22, v26, v27
	v_cvt_pk_bf16_f32 v23, v24, v25
	v_mov_b64_e32 v[24:25], s[68:69]
	v_mad_i64_i32 v[24:25], s[6:7], v18, s47, v[24:25]
	v_lshl_add_u64 v[24:25], v[146:147], 1, v[24:25]
	global_store_dwordx4 v[24:25], v[20:23], off nt
	s_mov_b64 s[6:7], 0
	v_pk_mul_f32 v[26:27], v[10:11], v[16:17] op_sel_hi:[1,0]
	v_pk_mul_f32 v[22:23], v[14:15], v[16:17] op_sel_hi:[1,0]
	v_pk_mul_f32 v[20:21], v[12:13], v[16:17] op_sel_hi:[1,0]
	s_nop 0
	v_cvt_pk_bf16_f32 v20, v20, v21
	v_cvt_pk_bf16_f32 v21, v22, v23
	v_cvt_pk_bf16_f32 v22, v28, v29
	v_cvt_pk_bf16_f32 v23, v26, v27
	global_store_dwordx4 v[24:25], v[20:23], off offset:256 nt
.LBB0_952:
	s_andn2_b64 vcc, exec, s[6:7]
	s_cbranch_vccnz .LBB0_954
	s_waitcnt lgkmcnt(0)
	v_mul_f32_e32 v17, 0xbfb8aa3b, v16
	v_mul_f32_e32 v20, v5, v17
	v_exp_f32_e32 v21, v20
	v_mul_f32_e32 v20, v6, v17
	v_mul_f32_e32 v19, v4, v17
	v_exp_f32_e32 v22, v20
	v_mul_f32_e32 v20, v7, v17
	v_exp_f32_e32 v19, v19
	v_exp_f32_e32 v23, v20
	v_mul_f32_e32 v12, v12, v17
	v_mul_f32_e32 v13, v13, v17
	v_mul_f32_e32 v14, v14, v17
	v_mul_f32_e32 v15, v15, v17
	v_exp_f32_e32 v12, v12
	v_exp_f32_e32 v13, v13
	v_exp_f32_e32 v14, v14
	v_exp_f32_e32 v15, v15
	v_add_f32_e32 v19, 1.0, v19
	v_add_f32_e32 v21, 1.0, v21
	v_add_f32_e32 v22, 1.0, v22
	v_add_f32_e32 v23, 1.0, v23
	v_rcp_f32_e32 v20, v19
	v_rcp_f32_e32 v21, v21
	v_rcp_f32_e32 v22, v22
	v_rcp_f32_e32 v23, v23
	v_pk_add_f32 v[14:15], v[14:15], 1.0 op_sel_hi:[1,0]
	v_pk_add_f32 v[12:13], v[12:13], 1.0 op_sel_hi:[1,0]
	v_rcp_f32_e32 v25, v14
	v_rcp_f32_e32 v19, v12
	v_rcp_f32_e32 v24, v13
	v_rcp_f32_e32 v26, v15
	v_pk_mul_f32 v[14:15], v[14:15], v[22:23]
	v_pk_mul_f32 v[12:13], v[12:13], v[20:21]
	v_mul_f32_e32 v20, v0, v17
	v_mul_f32_e32 v8, v8, v17
	v_mul_f32_e32 v21, v1, v17
	v_mul_f32_e32 v9, v9, v17
	v_mul_f32_e32 v22, v2, v17
	v_mul_f32_e32 v10, v10, v17
	v_mul_f32_e32 v11, v11, v17
	v_mul_f32_e32 v17, v3, v17
	v_exp_f32_e32 v20, v20
	v_exp_f32_e32 v21, v21
	v_exp_f32_e32 v22, v22
	v_exp_f32_e32 v17, v17
	v_exp_f32_e32 v8, v8
	v_exp_f32_e32 v9, v9
	v_exp_f32_e32 v10, v10
	v_exp_f32_e32 v11, v11
	v_add_f32_e32 v20, 1.0, v20
	v_add_f32_e32 v21, 1.0, v21
	v_add_f32_e32 v22, 1.0, v22
	v_add_f32_e32 v17, 1.0, v17
	v_rcp_f32_e32 v20, v20
	v_rcp_f32_e32 v21, v21
	v_rcp_f32_e32 v22, v22
	v_rcp_f32_e32 v23, v17
	v_pk_add_f32 v[10:11], v[10:11], 1.0 op_sel_hi:[1,0]
	v_pk_add_f32 v[8:9], v[8:9], 1.0 op_sel_hi:[1,0]
	v_rcp_f32_e32 v28, v10
	v_rcp_f32_e32 v27, v8
	v_rcp_f32_e32 v29, v11
	v_pk_mul_f32 v[22:23], v[10:11], v[22:23]
	v_pk_mul_f32 v[10:11], v[8:9], v[20:21]
	v_cvt_pk_bf16_f32 v8, v12, v13
	v_mov_b64_e32 v[12:13], s[68:69]
	v_lshl_add_u32 v136, s8, 7, v156
	v_mad_i64_i32 v[12:13], s[6:7], v18, s47, v[12:13]
	v_lshl_add_u64 v[12:13], v[136:137], 1, v[12:13]
	v_add_co_u32_e32 v12, vcc, 0x1000, v12
	v_rcp_f32_e32 v17, v9
	v_cvt_pk_bf16_f32 v9, v14, v15
	v_cvt_pk_bf16_f32 v10, v10, v11
	v_cvt_pk_bf16_f32 v11, v22, v23
	s_nop 0
	v_addc_co_u32_e32 v13, vcc, 0, v13, vcc
	global_store_dwordx4 v[12:13], v[8:11], off offset:512 nt
	s_nop 1
	v_cvt_pk_bf16_f32 v8, v19, v24
	v_cvt_pk_bf16_f32 v9, v25, v26
	v_cvt_pk_bf16_f32 v10, v27, v17
	v_cvt_pk_bf16_f32 v11, v28, v29
	global_store_dwordx4 v[12:13], v[8:11], off offset:2560 nt

;     __device__ __forceinline__ void operator()(Acc& acc, const Unit& u, int wr, int wc, int fr, int fq) const {
;     ...
;                 if (gate_tile) {
;                     if (wc == 0 && fq == 0) { *(f32x4*)(gates + (size_t)row * 8) = acc[ai][0][m][0] * r; *(f32x4*)(gates + (size_t)row * 8 + 4) = acc[ai][0][m][1] * r; }
.LBB0_955:
	s_and_saveexec_b64 s[6:7], s[2:3]
	s_cbranch_execz .LBB0_957
	v_ashrrev_i32_e32 v19, 31, v18
	v_lshlrev_b64 v[8:9], 5, v[18:19]
	v_lshl_add_u64 v[8:9], s[12:13], 0, v[8:9]
	s_waitcnt lgkmcnt(0)
	v_pk_mul_f32 v[6:7], v[6:7], v[16:17] op_sel_hi:[1,0]
	v_pk_mul_f32 v[4:5], v[4:5], v[16:17] op_sel_hi:[1,0]
	v_pk_mul_f32 v[2:3], v[2:3], v[16:17] op_sel_hi:[1,0]
	v_pk_mul_f32 v[0:1], v[0:1], v[16:17] op_sel_hi:[1,0]
	global_store_dwordx4 v[8:9], v[4:7], off nt
	global_store_dwordx4 v[8:9], v[0:3], off offset:16 nt
